# G4 residual epilogue: hand-written batched path (rolling window of 8 residual loads in dead fragment registers, counted vmcnt, stores at the end) instead of the serialized load-wait-store ladder
# speedup vs baseline: 1.0045x; 1.0045x over previous
; __device__ __forceinline__ unsigned cvt_pk_bf16(float lo, float hi) { unsigned r; asm volatile("v_cvt_pk_bf16_f32 %0, %1, %2" : "=v"(r) : "v"(lo), "v"(hi)); return r; }
;     __device__ __forceinline__ void operator()(const f32x4 (&acc)[2][2][4][2], const Unit& u, int wr, int wc, int fr, int fq) const {
;         const bool lat = u.pm < NLAT / BM; const int bb = lat ? (u.pm >> 5) : 4;
;         const int row0 = (lat ? u.pm * BM : u.pm * BM - NLAT) + wr * 64 + fr, col0 = u.pn * BM + wc * 32 + 8 * fq;
;         f32x4 g[2][2];
; #pragma unroll
;         for (int bj = 0; bj < 2; ++bj)
; #pragma unroll
;             for (int n = 0; n < 2; ++n) g[bj][n] = *(const f32x4*)(gate + bb * 6144 + col0 + bj * HALF + n * 4);
; #pragma unroll
;         for (int ai = 0; ai < 2; ++ai)
; #pragma unroll
;             for (int m = 0; m < 4; ++m) {
;                 const size_t off = (size_t)(row0 + ai * HALF + m * 16) * 1024 + col0;
; #pragma unroll
;                 for (int bj = 0; bj < 2; ++bj) {
;                     f32x4 b0, b1;
;                     if (!lat) { b0 = *(const f32x4*)(baseC + off + bj * HALF); b1 = *(const f32x4*)(baseC + off + bj * HALF + 4); }
;                     else if (baseLf) { b0 = *(const f32x4*)(baseLf + off + bj * HALF); b1 = *(const f32x4*)(baseLf + off + bj * HALF + 4); }
;                     else { const u32x4 w = *(const u32x4*)(baseLb + off + bj * HALF);
;                         b0 = (f32x4){__builtin_bit_cast(float, w.x << 16), __builtin_bit_cast(float, w.x & 0xffff0000u), __builtin_bit_cast(float, w.y << 16), __builtin_bit_cast(float, w.y & 0xffff0000u)};
;                         b1 = (f32x4){__builtin_bit_cast(float, w.z << 16), __builtin_bit_cast(float, w.z & 0xffff0000u), __builtin_bit_cast(float, w.w << 16), __builtin_bit_cast(float, w.w & 0xffff0000u)}; }
;                     const f32x4 o0 = b0 + g[bj][0] * acc[ai][bj][m][0], o1 = b1 + g[bj][1] * acc[ai][bj][m][1];
;                     if (!lat) { *(f32x4*)(outC + off + bj * HALF) = o0; *(f32x4*)(outC + off + bj * HALF + 4) = o1; }
;                     else { u32x4 w; w.x = cvt_pk_bf16(o0.x, o0.y); w.y = cvt_pk_bf16(o0.z, o0.w); w.z = cvt_pk_bf16(o1.x, o1.y); w.w = cvt_pk_bf16(o1.z, o1.w); *(u32x4*)(outL + off + bj * HALF) = w; }
;                 }
;             }
;     }
.LBB0_993:
	s_cmpk_gt_i32 s63, 0x7f
	s_cselect_b64 s[48:49], -1, 0
	s_lshl_b32 s15, s63, 8
	s_lshr_b32 s14, s63, 5
	s_add_i32 s16, s15, 0xffff8000
	s_cmpk_lt_i32 s63, 0x80
	s_cselect_b64 s[12:13], -1, 0
	s_mulk_i32 s14, 0x1800
	s_and_b64 vcc, s[12:13], exec
	s_cselect_b32 s12, s14, 0x6000
	s_cselect_b32 s14, s15, s16
	s_ashr_i32 s13, s12, 31
	s_lshl_b64 s[12:13], s[12:13], 2
	v_lshl_or_b32 v162, s62, 8, v172
	s_add_u32 s12, s42, s12
	s_addc_u32 s13, s43, s13
	v_ashrrev_i32_e32 v163, 31, v162
	v_lshl_add_u64 v[60:61], v[162:163], 2, s[12:13]
	global_load_dwordx4 v[72:75], v[60:61], off offset:16
	global_load_dwordx4 v[76:79], v[60:61], off
	global_load_dwordx4 v[56:59], v[60:61], off offset:528
	s_nop 0
	global_load_dwordx4 v[60:63], v[60:61], off offset:512
	v_add_u32_e32 v164, s14, v170
	v_ashrrev_i32_e32 v165, 31, v164
	v_lshlrev_b64 v[144:145], 10, v[164:165]
	v_lshl_add_u64 v[168:169], v[144:145], 0, v[162:163]
	s_mov_b64 s[40:41], -1
	v_lshl_add_u64 v[166:167], v[168:169], 2, s[26:27]
	s_cbranch_vccz .Lep4_slow
	v_lshl_add_u64 v[168:169], v[168:169], 1, s[6:7]
	s_mov_b64 s[12:13], 0x8000
	s_mov_b64 s[14:15], 0x28000
	v_mov_b32_e32 v164, v168
	v_mov_b32_e32 v165, v169
	global_load_dwordx4 v[174:177], v[168:169], off
	global_load_dwordx4 v[178:181], v[168:169], off offset:256
	v_lshl_add_u64 v[168:169], v[168:169], 0, s[12:13]
	global_load_dwordx4 v[182:185], v[168:169], off
	global_load_dwordx4 v[186:189], v[168:169], off offset:256
	v_lshl_add_u64 v[168:169], v[168:169], 0, s[12:13]
	global_load_dwordx4 v[190:193], v[168:169], off
	global_load_dwordx4 v[194:197], v[168:169], off offset:256
	v_lshl_add_u64 v[168:169], v[168:169], 0, s[12:13]
	global_load_dwordx4 v[198:201], v[168:169], off
	global_load_dwordx4 v[202:205], v[168:169], off offset:256
	s_waitcnt vmcnt(7)
	v_lshlrev_b32_e32 v144, 16, v174
	v_and_b32_e32 v145, 0xffff0000, v174
	v_lshlrev_b32_e32 v146, 16, v175
	v_and_b32_e32 v147, 0xffff0000, v175
	v_lshlrev_b32_e32 v148, 16, v176
	v_and_b32_e32 v149, 0xffff0000, v176
	v_lshlrev_b32_e32 v150, 16, v177
	v_and_b32_e32 v151, 0xffff0000, v177
	v_lshl_add_u64 v[168:169], v[168:169], 0, s[14:15]
	global_load_dwordx4 v[174:177], v[168:169], off
	v_pk_fma_f32 v[140:141], v[140:141], v[76:77], v[144:145]
	v_pk_fma_f32 v[142:143], v[142:143], v[78:79], v[146:147]
	v_pk_fma_f32 v[136:137], v[136:137], v[72:73], v[148:149]
	v_pk_fma_f32 v[138:139], v[138:139], v[74:75], v[150:151]
	v_cvt_pk_bf16_f32 v140, v140, v141
	v_cvt_pk_bf16_f32 v141, v142, v143
	v_cvt_pk_bf16_f32 v142, v136, v137
	v_cvt_pk_bf16_f32 v143, v138, v139
	s_waitcnt vmcnt(7)
	v_lshlrev_b32_e32 v144, 16, v178
	v_and_b32_e32 v145, 0xffff0000, v178
	v_lshlrev_b32_e32 v146, 16, v179
	v_and_b32_e32 v147, 0xffff0000, v179
	v_lshlrev_b32_e32 v148, 16, v180
	v_and_b32_e32 v149, 0xffff0000, v180
	v_lshlrev_b32_e32 v150, 16, v181
	v_and_b32_e32 v151, 0xffff0000, v181
	global_load_dwordx4 v[178:181], v[168:169], off offset:256
	v_pk_fma_f32 v[132:133], v[132:133], v[60:61], v[144:145]
	v_pk_fma_f32 v[134:135], v[134:135], v[62:63], v[146:147]
	v_pk_fma_f32 v[128:129], v[128:129], v[56:57], v[148:149]
	v_pk_fma_f32 v[130:131], v[130:131], v[58:59], v[150:151]
	v_cvt_pk_bf16_f32 v132, v132, v133
	v_cvt_pk_bf16_f32 v133, v134, v135
	v_cvt_pk_bf16_f32 v134, v128, v129
	v_cvt_pk_bf16_f32 v135, v130, v131
	s_waitcnt vmcnt(7)
	v_lshlrev_b32_e32 v144, 16, v182
	v_and_b32_e32 v145, 0xffff0000, v182
	v_lshlrev_b32_e32 v146, 16, v183
	v_and_b32_e32 v147, 0xffff0000, v183
	v_lshlrev_b32_e32 v148, 16, v184
	v_and_b32_e32 v149, 0xffff0000, v184
	v_lshlrev_b32_e32 v150, 16, v185
	v_and_b32_e32 v151, 0xffff0000, v185
	v_lshl_add_u64 v[168:169], v[168:169], 0, s[12:13]
	global_load_dwordx4 v[182:185], v[168:169], off
	v_pk_fma_f32 v[124:125], v[124:125], v[76:77], v[144:145]
	v_pk_fma_f32 v[126:127], v[126:127], v[78:79], v[146:147]
	v_pk_fma_f32 v[120:121], v[120:121], v[72:73], v[148:149]
	v_pk_fma_f32 v[122:123], v[122:123], v[74:75], v[150:151]
	v_cvt_pk_bf16_f32 v124, v124, v125
	v_cvt_pk_bf16_f32 v125, v126, v127
	v_cvt_pk_bf16_f32 v126, v120, v121
	v_cvt_pk_bf16_f32 v127, v122, v123
	s_waitcnt vmcnt(7)
	v_lshlrev_b32_e32 v144, 16, v186
	v_and_b32_e32 v145, 0xffff0000, v186
	v_lshlrev_b32_e32 v146, 16, v187
	v_and_b32_e32 v147, 0xffff0000, v187
	v_lshlrev_b32_e32 v148, 16, v188
	v_and_b32_e32 v149, 0xffff0000, v188
	v_lshlrev_b32_e32 v150, 16, v189
	v_and_b32_e32 v151, 0xffff0000, v189
	global_load_dwordx4 v[186:189], v[168:169], off offset:256
	v_pk_fma_f32 v[116:117], v[116:117], v[60:61], v[144:145]
	v_pk_fma_f32 v[118:119], v[118:119], v[62:63], v[146:147]
	v_pk_fma_f32 v[112:113], v[112:113], v[56:57], v[148:149]
	v_pk_fma_f32 v[114:115], v[114:115], v[58:59], v[150:151]
	v_cvt_pk_bf16_f32 v116, v116, v117
	v_cvt_pk_bf16_f32 v117, v118, v119
	v_cvt_pk_bf16_f32 v118, v112, v113
	v_cvt_pk_bf16_f32 v119, v114, v115
	s_waitcnt vmcnt(7)
	v_lshlrev_b32_e32 v144, 16, v190
	v_and_b32_e32 v145, 0xffff0000, v190
	v_lshlrev_b32_e32 v146, 16, v191
	v_and_b32_e32 v147, 0xffff0000, v191
	v_lshlrev_b32_e32 v148, 16, v192
	v_and_b32_e32 v149, 0xffff0000, v192
	v_lshlrev_b32_e32 v150, 16, v193
	v_and_b32_e32 v151, 0xffff0000, v193
	v_lshl_add_u64 v[168:169], v[168:169], 0, s[12:13]
	global_load_dwordx4 v[190:193], v[168:169], off
	v_pk_fma_f32 v[108:109], v[108:109], v[76:77], v[144:145]
	v_pk_fma_f32 v[110:111], v[110:111], v[78:79], v[146:147]
	v_pk_fma_f32 v[104:105], v[104:105], v[72:73], v[148:149]
	v_pk_fma_f32 v[106:107], v[106:107], v[74:75], v[150:151]
	v_cvt_pk_bf16_f32 v108, v108, v109
	v_cvt_pk_bf16_f32 v109, v110, v111
	v_cvt_pk_bf16_f32 v110, v104, v105
	v_cvt_pk_bf16_f32 v111, v106, v107
	s_waitcnt vmcnt(7)
; __device__ __forceinline__ unsigned cvt_pk_bf16(float lo, float hi) { unsigned r; asm volatile("v_cvt_pk_bf16_f32 %0, %1, %2" : "=v"(r) : "v"(lo), "v"(hi)); return r; }
;     __device__ __forceinline__ void operator()(const f32x4 (&acc)[2][2][4][2], const Unit& u, int wr, int wc, int fr, int fq) const {
;     ...
;                 for (int bj = 0; bj < 2; ++bj) {
;                     f32x4 b0, b1;
;                     if (!lat) { b0 = *(const f32x4*)(baseC + off + bj * HALF); b1 = *(const f32x4*)(baseC + off + bj * HALF + 4); }
;                     else if (baseLf) { b0 = *(const f32x4*)(baseLf + off + bj * HALF); b1 = *(const f32x4*)(baseLf + off + bj * HALF + 4); }
;                     else { const u32x4 w = *(const u32x4*)(baseLb + off + bj * HALF);
;                         b0 = (f32x4){__builtin_bit_cast(float, w.x << 16), __builtin_bit_cast(float, w.x & 0xffff0000u), __builtin_bit_cast(float, w.y << 16), __builtin_bit_cast(float, w.y & 0xffff0000u)};
;                         b1 = (f32x4){__builtin_bit_cast(float, w.z << 16), __builtin_bit_cast(float, w.z & 0xffff0000u), __builtin_bit_cast(float, w.w << 16), __builtin_bit_cast(float, w.w & 0xffff0000u)}; }
;                     const f32x4 o0 = b0 + g[bj][0] * acc[ai][bj][m][0], o1 = b1 + g[bj][1] * acc[ai][bj][m][1];
;                     if (!lat) { *(f32x4*)(outC + off + bj * HALF) = o0; *(f32x4*)(outC + off + bj * HALF + 4) = o1; }
;                     else { u32x4 w; w.x = cvt_pk_bf16(o0.x, o0.y); w.y = cvt_pk_bf16(o0.z, o0.w); w.z = cvt_pk_bf16(o1.x, o1.y); w.w = cvt_pk_bf16(o1.z, o1.w); *(u32x4*)(outL + off + bj * HALF) = w; }
;                 }
	v_lshlrev_b32_e32 v144, 16, v194
	v_and_b32_e32 v145, 0xffff0000, v194
	v_lshlrev_b32_e32 v146, 16, v195
	v_and_b32_e32 v147, 0xffff0000, v195
	v_lshlrev_b32_e32 v148, 16, v196
	v_and_b32_e32 v149, 0xffff0000, v196
	v_lshlrev_b32_e32 v150, 16, v197
	v_and_b32_e32 v151, 0xffff0000, v197
	global_load_dwordx4 v[194:197], v[168:169], off offset:256
	v_pk_fma_f32 v[100:101], v[100:101], v[60:61], v[144:145]
	v_pk_fma_f32 v[102:103], v[102:103], v[62:63], v[146:147]
	v_pk_fma_f32 v[96:97], v[96:97], v[56:57], v[148:149]
	v_pk_fma_f32 v[98:99], v[98:99], v[58:59], v[150:151]
	v_cvt_pk_bf16_f32 v100, v100, v101
	v_cvt_pk_bf16_f32 v101, v102, v103
	v_cvt_pk_bf16_f32 v102, v96, v97
	v_cvt_pk_bf16_f32 v103, v98, v99
	s_waitcnt vmcnt(7)
	v_lshlrev_b32_e32 v144, 16, v198
	v_and_b32_e32 v145, 0xffff0000, v198
	v_lshlrev_b32_e32 v146, 16, v199
	v_and_b32_e32 v147, 0xffff0000, v199
	v_lshlrev_b32_e32 v148, 16, v200
	v_and_b32_e32 v149, 0xffff0000, v200
	v_lshlrev_b32_e32 v150, 16, v201
	v_and_b32_e32 v151, 0xffff0000, v201
	v_lshl_add_u64 v[168:169], v[168:169], 0, s[12:13]
	global_load_dwordx4 v[198:201], v[168:169], off
	v_pk_fma_f32 v[92:93], v[92:93], v[76:77], v[144:145]
	v_pk_fma_f32 v[94:95], v[94:95], v[78:79], v[146:147]
	v_pk_fma_f32 v[88:89], v[88:89], v[72:73], v[148:149]
	v_pk_fma_f32 v[90:91], v[90:91], v[74:75], v[150:151]
	v_cvt_pk_bf16_f32 v92, v92, v93
	v_cvt_pk_bf16_f32 v93, v94, v95
	v_cvt_pk_bf16_f32 v94, v88, v89
	v_cvt_pk_bf16_f32 v95, v90, v91
	s_waitcnt vmcnt(7)
	v_lshlrev_b32_e32 v144, 16, v202
	v_and_b32_e32 v145, 0xffff0000, v202
	v_lshlrev_b32_e32 v146, 16, v203
	v_and_b32_e32 v147, 0xffff0000, v203
	v_lshlrev_b32_e32 v148, 16, v204
	v_and_b32_e32 v149, 0xffff0000, v204
	v_lshlrev_b32_e32 v150, 16, v205
	v_and_b32_e32 v151, 0xffff0000, v205
	global_load_dwordx4 v[202:205], v[168:169], off offset:256
	v_pk_fma_f32 v[84:85], v[84:85], v[60:61], v[144:145]
	v_pk_fma_f32 v[86:87], v[86:87], v[62:63], v[146:147]
	v_pk_fma_f32 v[80:81], v[80:81], v[56:57], v[148:149]
	v_pk_fma_f32 v[82:83], v[82:83], v[58:59], v[150:151]
	v_cvt_pk_bf16_f32 v84, v84, v85
	v_cvt_pk_bf16_f32 v85, v86, v87
	v_cvt_pk_bf16_f32 v86, v80, v81
	v_cvt_pk_bf16_f32 v87, v82, v83
	s_waitcnt vmcnt(7)
	v_lshlrev_b32_e32 v144, 16, v174
	v_and_b32_e32 v145, 0xffff0000, v174
	v_lshlrev_b32_e32 v146, 16, v175
	v_and_b32_e32 v147, 0xffff0000, v175
	v_lshlrev_b32_e32 v148, 16, v176
	v_and_b32_e32 v149, 0xffff0000, v176
	v_lshlrev_b32_e32 v150, 16, v177
	v_and_b32_e32 v151, 0xffff0000, v177
	v_pk_fma_f32 v[68:69], v[68:69], v[76:77], v[144:145]
	v_pk_fma_f32 v[70:71], v[70:71], v[78:79], v[146:147]
	v_pk_fma_f32 v[64:65], v[64:65], v[72:73], v[148:149]
	v_pk_fma_f32 v[66:67], v[66:67], v[74:75], v[150:151]
	v_cvt_pk_bf16_f32 v68, v68, v69
	v_cvt_pk_bf16_f32 v69, v70, v71
	v_cvt_pk_bf16_f32 v70, v64, v65
	v_cvt_pk_bf16_f32 v71, v66, v67
	s_waitcnt vmcnt(6)
	v_lshlrev_b32_e32 v144, 16, v178
	v_and_b32_e32 v145, 0xffff0000, v178
	v_lshlrev_b32_e32 v146, 16, v179
	v_and_b32_e32 v147, 0xffff0000, v179
	v_lshlrev_b32_e32 v148, 16, v180
	v_and_b32_e32 v149, 0xffff0000, v180
	v_lshlrev_b32_e32 v150, 16, v181
	v_and_b32_e32 v151, 0xffff0000, v181
	v_pk_fma_f32 v[52:53], v[52:53], v[60:61], v[144:145]
	v_pk_fma_f32 v[54:55], v[54:55], v[62:63], v[146:147]
	v_pk_fma_f32 v[48:49], v[48:49], v[56:57], v[148:149]
	v_pk_fma_f32 v[50:51], v[50:51], v[58:59], v[150:151]
	v_cvt_pk_bf16_f32 v52, v52, v53
	v_cvt_pk_bf16_f32 v53, v54, v55
	v_cvt_pk_bf16_f32 v54, v48, v49
	v_cvt_pk_bf16_f32 v55, v50, v51
	s_waitcnt vmcnt(5)
	v_lshlrev_b32_e32 v144, 16, v182
	v_and_b32_e32 v145, 0xffff0000, v182
	v_lshlrev_b32_e32 v146, 16, v183
	v_and_b32_e32 v147, 0xffff0000, v183
	v_lshlrev_b32_e32 v148, 16, v184
	v_and_b32_e32 v149, 0xffff0000, v184
	v_lshlrev_b32_e32 v150, 16, v185
	v_and_b32_e32 v151, 0xffff0000, v185
	v_pk_fma_f32 v[44:45], v[44:45], v[76:77], v[144:145]
	v_pk_fma_f32 v[46:47], v[46:47], v[78:79], v[146:147]
	v_pk_fma_f32 v[40:41], v[40:41], v[72:73], v[148:149]
	v_pk_fma_f32 v[42:43], v[42:43], v[74:75], v[150:151]
	v_cvt_pk_bf16_f32 v44, v44, v45
	v_cvt_pk_bf16_f32 v45, v46, v47
	v_cvt_pk_bf16_f32 v46, v40, v41
	v_cvt_pk_bf16_f32 v47, v42, v43
	s_waitcnt vmcnt(4)
; __device__ __forceinline__ unsigned cvt_pk_bf16(float lo, float hi) { unsigned r; asm volatile("v_cvt_pk_bf16_f32 %0, %1, %2" : "=v"(r) : "v"(lo), "v"(hi)); return r; }
;     __device__ __forceinline__ void operator()(const f32x4 (&acc)[2][2][4][2], const Unit& u, int wr, int wc, int fr, int fq) const {
;     ...
;                 for (int bj = 0; bj < 2; ++bj) {
;                     f32x4 b0, b1;
;                     if (!lat) { b0 = *(const f32x4*)(baseC + off + bj * HALF); b1 = *(const f32x4*)(baseC + off + bj * HALF + 4); }
;                     else if (baseLf) { b0 = *(const f32x4*)(baseLf + off + bj * HALF); b1 = *(const f32x4*)(baseLf + off + bj * HALF + 4); }
;                     else { const u32x4 w = *(const u32x4*)(baseLb + off + bj * HALF);
;                         b0 = (f32x4){__builtin_bit_cast(float, w.x << 16), __builtin_bit_cast(float, w.x & 0xffff0000u), __builtin_bit_cast(float, w.y << 16), __builtin_bit_cast(float, w.y & 0xffff0000u)};
;                         b1 = (f32x4){__builtin_bit_cast(float, w.z << 16), __builtin_bit_cast(float, w.z & 0xffff0000u), __builtin_bit_cast(float, w.w << 16), __builtin_bit_cast(float, w.w & 0xffff0000u)}; }
;                     const f32x4 o0 = b0 + g[bj][0] * acc[ai][bj][m][0], o1 = b1 + g[bj][1] * acc[ai][bj][m][1];
;                     if (!lat) { *(f32x4*)(outC + off + bj * HALF) = o0; *(f32x4*)(outC + off + bj * HALF + 4) = o1; }
;                     else { u32x4 w; w.x = cvt_pk_bf16(o0.x, o0.y); w.y = cvt_pk_bf16(o0.z, o0.w); w.z = cvt_pk_bf16(o1.x, o1.y); w.w = cvt_pk_bf16(o1.z, o1.w); *(u32x4*)(outL + off + bj * HALF) = w; }
;                 }
	v_lshlrev_b32_e32 v144, 16, v186
	v_and_b32_e32 v145, 0xffff0000, v186
	v_lshlrev_b32_e32 v146, 16, v187
	v_and_b32_e32 v147, 0xffff0000, v187
	v_lshlrev_b32_e32 v148, 16, v188
	v_and_b32_e32 v149, 0xffff0000, v188
	v_lshlrev_b32_e32 v150, 16, v189
	v_and_b32_e32 v151, 0xffff0000, v189
	v_pk_fma_f32 v[36:37], v[36:37], v[60:61], v[144:145]
	v_pk_fma_f32 v[38:39], v[38:39], v[62:63], v[146:147]
	v_pk_fma_f32 v[32:33], v[32:33], v[56:57], v[148:149]
	v_pk_fma_f32 v[34:35], v[34:35], v[58:59], v[150:151]
	v_cvt_pk_bf16_f32 v36, v36, v37
	v_cvt_pk_bf16_f32 v37, v38, v39
	v_cvt_pk_bf16_f32 v38, v32, v33
	v_cvt_pk_bf16_f32 v39, v34, v35
	s_waitcnt vmcnt(3)
	v_lshlrev_b32_e32 v144, 16, v190
	v_and_b32_e32 v145, 0xffff0000, v190
	v_lshlrev_b32_e32 v146, 16, v191
	v_and_b32_e32 v147, 0xffff0000, v191
	v_lshlrev_b32_e32 v148, 16, v192
	v_and_b32_e32 v149, 0xffff0000, v192
	v_lshlrev_b32_e32 v150, 16, v193
	v_and_b32_e32 v151, 0xffff0000, v193
	v_pk_fma_f32 v[28:29], v[28:29], v[76:77], v[144:145]
	v_pk_fma_f32 v[30:31], v[30:31], v[78:79], v[146:147]
	v_pk_fma_f32 v[24:25], v[24:25], v[72:73], v[148:149]
	v_pk_fma_f32 v[26:27], v[26:27], v[74:75], v[150:151]
	v_cvt_pk_bf16_f32 v28, v28, v29
	v_cvt_pk_bf16_f32 v29, v30, v31
	v_cvt_pk_bf16_f32 v30, v24, v25
	v_cvt_pk_bf16_f32 v31, v26, v27
	s_waitcnt vmcnt(2)
	v_lshlrev_b32_e32 v144, 16, v194
	v_and_b32_e32 v145, 0xffff0000, v194
	v_lshlrev_b32_e32 v146, 16, v195
	v_and_b32_e32 v147, 0xffff0000, v195
	v_lshlrev_b32_e32 v148, 16, v196
	v_and_b32_e32 v149, 0xffff0000, v196
	v_lshlrev_b32_e32 v150, 16, v197
	v_and_b32_e32 v151, 0xffff0000, v197
	v_pk_fma_f32 v[20:21], v[20:21], v[60:61], v[144:145]
	v_pk_fma_f32 v[22:23], v[22:23], v[62:63], v[146:147]
	v_pk_fma_f32 v[16:17], v[16:17], v[56:57], v[148:149]
	v_pk_fma_f32 v[18:19], v[18:19], v[58:59], v[150:151]
	v_cvt_pk_bf16_f32 v20, v20, v21
	v_cvt_pk_bf16_f32 v21, v22, v23
	v_cvt_pk_bf16_f32 v22, v16, v17
	v_cvt_pk_bf16_f32 v23, v18, v19
	s_waitcnt vmcnt(1)
	v_lshlrev_b32_e32 v144, 16, v198
	v_and_b32_e32 v145, 0xffff0000, v198
	v_lshlrev_b32_e32 v146, 16, v199
	v_and_b32_e32 v147, 0xffff0000, v199
	v_lshlrev_b32_e32 v148, 16, v200
	v_and_b32_e32 v149, 0xffff0000, v200
	v_lshlrev_b32_e32 v150, 16, v201
	v_and_b32_e32 v151, 0xffff0000, v201
	v_pk_fma_f32 v[12:13], v[12:13], v[76:77], v[144:145]
	v_pk_fma_f32 v[14:15], v[14:15], v[78:79], v[146:147]
	v_pk_fma_f32 v[8:9], v[8:9], v[72:73], v[148:149]
	v_pk_fma_f32 v[10:11], v[10:11], v[74:75], v[150:151]
	v_cvt_pk_bf16_f32 v12, v12, v13
	v_cvt_pk_bf16_f32 v13, v14, v15
	v_cvt_pk_bf16_f32 v14, v8, v9
	v_cvt_pk_bf16_f32 v15, v10, v11
	s_waitcnt vmcnt(0)
	v_lshlrev_b32_e32 v144, 16, v202
	v_and_b32_e32 v145, 0xffff0000, v202
	v_lshlrev_b32_e32 v146, 16, v203
	v_and_b32_e32 v147, 0xffff0000, v203
	v_lshlrev_b32_e32 v148, 16, v204
	v_and_b32_e32 v149, 0xffff0000, v204
	v_lshlrev_b32_e32 v150, 16, v205
	v_and_b32_e32 v151, 0xffff0000, v205
	v_pk_fma_f32 v[4:5], v[4:5], v[60:61], v[144:145]
	v_pk_fma_f32 v[6:7], v[6:7], v[62:63], v[146:147]
	v_pk_fma_f32 v[0:1], v[0:1], v[56:57], v[148:149]
	v_pk_fma_f32 v[2:3], v[2:3], v[58:59], v[150:151]
	v_cvt_pk_bf16_f32 v4, v4, v5
	v_cvt_pk_bf16_f32 v5, v6, v7
	v_cvt_pk_bf16_f32 v6, v0, v1
	v_cvt_pk_bf16_f32 v7, v2, v3
	global_store_dwordx4 v[164:165], v[140:143], off
	global_store_dwordx4 v[164:165], v[132:135], off offset:256
	v_lshl_add_u64 v[164:165], v[164:165], 0, s[12:13]
	global_store_dwordx4 v[164:165], v[124:127], off
	global_store_dwordx4 v[164:165], v[116:119], off offset:256
	v_lshl_add_u64 v[164:165], v[164:165], 0, s[12:13]
	global_store_dwordx4 v[164:165], v[108:111], off
	global_store_dwordx4 v[164:165], v[100:103], off offset:256
	v_lshl_add_u64 v[164:165], v[164:165], 0, s[12:13]
	global_store_dwordx4 v[164:165], v[92:95], off
	global_store_dwordx4 v[164:165], v[84:87], off offset:256
	v_lshl_add_u64 v[164:165], v[164:165], 0, s[14:15]
	global_store_dwordx4 v[164:165], v[68:71], off
	global_store_dwordx4 v[164:165], v[52:55], off offset:256
	v_lshl_add_u64 v[164:165], v[164:165], 0, s[12:13]
	global_store_dwordx4 v[164:165], v[44:47], off
	global_store_dwordx4 v[164:165], v[36:39], off offset:256
	v_lshl_add_u64 v[164:165], v[164:165], 0, s[12:13]
	global_store_dwordx4 v[164:165], v[28:31], off
	global_store_dwordx4 v[164:165], v[20:23], off offset:256
	v_lshl_add_u64 v[164:165], v[164:165], 0, s[12:13]
	global_store_dwordx4 v[164:165], v[12:15], off
	global_store_dwordx4 v[164:165], v[4:7], off offset:256
	s_mov_b64 s[40:41], -1
	s_mov_b64 s[48:49], -1
	s_branch .Lep4_join
.Lep4_slow:
	s_cbranch_vccnz .LBB0_995
	global_load_dwordx4 v[144:147], v[166:167], off offset:16
	global_load_dwordx4 v[148:151], v[166:167], off
	s_mov_b64 s[40:41], 0

; __device__ __forceinline__ unsigned cvt_pk_bf16(float lo, float hi) { unsigned r; asm volatile("v_cvt_pk_bf16_f32 %0, %1, %2" : "=v"(r) : "v"(lo), "v"(hi)); return r; }
;     __device__ __forceinline__ void operator()(const f32x4 (&acc)[2][2][4][2], const Unit& u, int wr, int wc, int fr, int fq) const {
;     ...
;                     const f32x4 o0 = b0 + g[bj][0] * acc[ai][bj][m][0], o1 = b1 + g[bj][1] * acc[ai][bj][m][1];
;                     if (!lat) { *(f32x4*)(outC + off + bj * HALF) = o0; *(f32x4*)(outC + off + bj * HALF + 4) = o1; }
;                     else { u32x4 w; w.x = cvt_pk_bf16(o0.x, o0.y); w.y = cvt_pk_bf16(o0.z, o0.w); w.z = cvt_pk_bf16(o1.x, o1.y); w.w = cvt_pk_bf16(o1.z, o1.w); *(u32x4*)(outL + off + bj * HALF) = w; }
;                 }
; template <class Epi, class Sched, bool ALIGN_EPI = false, bool SP2 = false>
; __device__ __forceinline__ void gemm_phase(PG8_LAS unsigned char* lds, const Gemm g, const Sched& S, const Epi& E) {
;     ...
;         if constexpr (!Epi::AFTER_DRAIN) { E(acc, cur, wr, wc, fr, fq); S.done(cur); }
;         if (!has_next) break;
.LBB0_1121:
	v_cvt_pk_bf16_f32 v4, v4, v5
	v_cvt_pk_bf16_f32 v5, v6, v7
	v_cvt_pk_bf16_f32 v6, v0, v1
	v_cvt_pk_bf16_f32 v7, v2, v3
	global_store_dwordx4 v[26:27], v[4:7], off offset:256
.Lep4_join:
	s_andn2_b64 vcc, exec, s[38:39]
	s_mov_b64 s[38:39], -1
	s_cbranch_vccnz .LBB0_982
.LBB0_1122:
	s_andn2_b64 vcc, exec, s[36:37]
	s_cbranch_vccnz .LBB0_981
	s_barrier
	s_branch .LBB0_981
